# attention row reductions: xor-16 step through v_permlane16_swap as well (no ds_bpermute left in the softmax)
# baseline (speedup 1.0000x reference)
.LBB0_1163:
	s_or_b64 exec, exec, s[16:17]
	v_lshlrev_b32_e32 v207, 7, v0
	v_mov_b32_e32 v0, s74
	v_cndmask_b32_e64 v0, v92, v0, s[38:39]
	v_cndmask_b32_e64 v0, v0, v92, s[36:37]
	v_max3_f32 v92, v99, s74, v98
	v_max3_f32 v92, v92, v2, v1
	v_max3_f32 v92, v92, v124, v125
	v_max3_f32 v92, v92, v126, v127
	v_max3_f32 v92, v92, v116, v117
	v_max3_f32 v92, v92, v118, v119
	v_max3_f32 v92, v92, v108, v109
	v_max3_f32 v92, v92, v110, v111
	v_max3_f32 v92, v92, v104, v105
	v_max3_f32 v92, v92, v106, v107
	v_max3_f32 v92, v92, v100, v101
	v_max3_f32 v92, v92, v102, v103
	v_max3_f32 v92, v92, v112, v113
	v_max3_f32 v92, v92, v114, v115
	v_and_b32_e32 v205, 64, v175
	v_max3_f32 v92, v92, v120, v121
	v_xor_b32_e32 v133, 16, v175
	v_add_u32_e32 v205, 64, v205
	v_cndmask_b32_e64 v93, v203, v93, s[36:37]
	v_max3_f32 v92, v92, v122, v123
	v_cmp_lt_i32_e32 vcc, v133, v205
	v_cndmask_b32_e64 v94, v94, v203, s[44:45]
	v_cndmask_b32_e64 v95, v95, v203, s[48:49]
	v_max3_f32 v92, v92, v0, v93
	v_cndmask_b32_e32 v133, v175, v133, vcc
	v_max3_f32 v92, v92, v94, v95
	v_lshlrev_b32_e32 v133, 2, v133
	v_mov_b32_e32 v209, v92
	s_nop 1
	v_permlane16_swap_b32_e32 v209, v92
	s_nop 0
	v_lshlrev_b32_e64 v96, v129, -1
	v_or_b32_e32 v97, v207, v155
	v_and_b32_e32 v208, 7, v135
	s_waitcnt lgkmcnt(0)
	v_max_f32_e32 v209, v209, v209
	v_max_f32_e32 v92, v92, v209
	v_xor_b32_e32 v209, 32, v175
	v_cmp_lt_i32_e32 vcc, v209, v205
	s_nop 1
	v_cndmask_b32_e32 v205, v175, v209, vcc
	v_lshlrev_b32_e32 v205, 2, v205
	v_mov_b32_e32 v209, v92
	s_nop 1
	v_permlane32_swap_b32_e32 v209, v92
	s_nop 0
	v_max_f32_e32 v209, v209, v209
	v_max_f32_e32 v92, v92, v209
	v_mul_f32_e32 v209, 0xbe38aa3b, v92
	v_fmamk_f32 v99, v99, 0x3e38aa3b, v209
	v_exp_f32_e32 v99, v99
	v_fmamk_f32 v98, v98, 0x3e38aa3b, v209
	v_exp_f32_e32 v98, v98
	v_fmamk_f32 v2, v2, 0x3e38aa3b, v209
	v_exp_f32_e32 v211, v2
	v_add_f32_e32 v210, 0, v99
	v_add_f32_e32 v210, v98, v210
	v_fmamk_f32 v1, v1, 0x3e38aa3b, v209
	v_add_f32_e32 v2, v211, v210
	v_exp_f32_e32 v210, v1
	v_cvt_pk_bf16_f32 v98, v99, v98
	v_fmamk_f32 v0, v0, 0x3e38aa3b, v209
	v_exp_f32_e32 v0, v0
	v_add_f32_e32 v1, v210, v2
	v_fmamk_f32 v2, v124, 0x3e38aa3b, v209
	v_exp_f32_e32 v124, v2
	v_fmamk_f32 v2, v125, 0x3e38aa3b, v209
	v_exp_f32_e32 v125, v2
	v_fmamk_f32 v2, v126, 0x3e38aa3b, v209
	v_exp_f32_e32 v126, v2
	v_fmamk_f32 v2, v127, 0x3e38aa3b, v209
	v_exp_f32_e32 v127, v2
	v_fmamk_f32 v2, v116, 0x3e38aa3b, v209
	v_exp_f32_e32 v212, v2
	v_fmamk_f32 v2, v117, 0x3e38aa3b, v209
	v_exp_f32_e32 v213, v2
	v_fmamk_f32 v2, v118, 0x3e38aa3b, v209
	v_exp_f32_e32 v118, v2
	v_fmamk_f32 v2, v119, 0x3e38aa3b, v209
	v_exp_f32_e32 v119, v2
	v_fmamk_f32 v2, v108, 0x3e38aa3b, v209
	v_exp_f32_e32 v214, v2
	v_fmamk_f32 v2, v109, 0x3e38aa3b, v209
	v_exp_f32_e32 v215, v2
	v_fmamk_f32 v2, v110, 0x3e38aa3b, v209
	v_exp_f32_e32 v216, v2
	v_fmamk_f32 v2, v111, 0x3e38aa3b, v209
	v_exp_f32_e32 v217, v2
	v_fmamk_f32 v2, v104, 0x3e38aa3b, v209
	v_exp_f32_e32 v218, v2
	v_fmamk_f32 v2, v105, 0x3e38aa3b, v209
	v_exp_f32_e32 v219, v2
	v_fmamk_f32 v2, v106, 0x3e38aa3b, v209
	v_exp_f32_e32 v220, v2
	v_fmamk_f32 v2, v107, 0x3e38aa3b, v209
	v_exp_f32_e32 v221, v2
	v_fmamk_f32 v2, v100, 0x3e38aa3b, v209
	v_exp_f32_e32 v222, v2
	v_fmamk_f32 v2, v101, 0x3e38aa3b, v209
	v_exp_f32_e32 v223, v2
	v_fmamk_f32 v2, v102, 0x3e38aa3b, v209
	v_exp_f32_e32 v224, v2
	v_fmamk_f32 v2, v103, 0x3e38aa3b, v209
	v_exp_f32_e32 v225, v2
	v_fmamk_f32 v2, v112, 0x3e38aa3b, v209
	v_add_f32_e32 v1, v124, v1
	v_exp_f32_e32 v226, v2
	v_fmamk_f32 v2, v113, 0x3e38aa3b, v209
	v_add_f32_e32 v1, v125, v1
	v_exp_f32_e32 v227, v2
	v_fmamk_f32 v2, v114, 0x3e38aa3b, v209
	v_add_f32_e32 v1, v126, v1
	v_exp_f32_e32 v228, v2
	v_fmamk_f32 v2, v115, 0x3e38aa3b, v209
	ds_read_b64_tr_b16 v[104:105], v177 offset:36864
	ds_read_b64_tr_b16 v[108:109], v177 offset:36896
	ds_read_b64_tr_b16 v[102:103], v176 offset:36864
	ds_read_b64_tr_b16 v[106:107], v176 offset:36896
	ds_read_b64_tr_b16 v[110:111], v176 offset:36928
	ds_read_b64_tr_b16 v[112:113], v177 offset:36928
	ds_read_b64_tr_b16 v[114:115], v176 offset:36960
	ds_read_b64_tr_b16 v[116:117], v177 offset:36960
	v_add_f32_e32 v1, v127, v1
	v_add_f32_e32 v1, v212, v1
	v_exp_f32_e32 v229, v2
	v_fmamk_f32 v2, v120, 0x3e38aa3b, v209
	v_add_f32_e32 v1, v213, v1
	v_exp_f32_e32 v230, v2
	v_fmamk_f32 v2, v121, 0x3e38aa3b, v209
	v_add_f32_e32 v1, v118, v1
	v_exp_f32_e32 v231, v2
	v_fmamk_f32 v2, v122, 0x3e38aa3b, v209
	v_cvt_pk_bf16_f32 v99, v211, v210
	v_cvt_pk_bf16_f32 v100, v124, v125
	v_cvt_pk_bf16_f32 v101, v126, v127
	v_add_f32_e32 v1, v119, v1
	v_exp_f32_e32 v232, v2
	v_fmamk_f32 v2, v123, 0x3e38aa3b, v209
	s_waitcnt lgkmcnt(5)
	v_mfma_f32_16x16x32_bf16 v[102:105], v[102:105], v[98:101], 0
	v_add_f32_e32 v1, v214, v1
	v_add_f32_e32 v1, v215, v1
	v_add_f32_e32 v1, v216, v1
	s_waitcnt lgkmcnt(4)
	v_mfma_f32_16x16x32_bf16 v[106:109], v[106:109], v[98:101], 0
	v_add_f32_e32 v1, v217, v1
	v_exp_f32_e32 v233, v2
	v_add_f32_e32 v1, v218, v1
	s_waitcnt lgkmcnt(2)
	v_mfma_f32_16x16x32_bf16 v[110:113], v[110:113], v[98:101], 0
	v_add_f32_e32 v1, v219, v1
	v_add_f32_e32 v1, v220, v1
	v_add_f32_e32 v1, v221, v1
	s_waitcnt lgkmcnt(0)
	v_mfma_f32_16x16x32_bf16 v[98:101], v[114:117], v[98:101], 0
	v_cvt_pk_bf16_f32 v115, v118, v119
	ds_read_b64_tr_b16 v[120:121], v179 offset:36864
	ds_read_b64_tr_b16 v[124:125], v179 offset:36896
	ds_read_b64_tr_b16 v[118:119], v178 offset:36864
	ds_read_b64_tr_b16 v[122:123], v178 offset:36896
	v_cvt_pk_bf16_f32 v114, v212, v213
	v_cvt_pk_bf16_f32 v116, v214, v215
	v_cvt_pk_bf16_f32 v117, v216, v217
	v_add_f32_e32 v1, v222, v1
	v_add_f32_e32 v1, v223, v1
	s_waitcnt lgkmcnt(1)
	v_mfma_f32_16x16x32_bf16 v[102:105], v[118:121], v[114:117], v[102:105]
	ds_read_b64_tr_b16 v[118:119], v178 offset:36928
	ds_read_b64_tr_b16 v[120:121], v179 offset:36928
	v_add_f32_e32 v1, v224, v1
	v_add_f32_e32 v1, v225, v1
	s_waitcnt lgkmcnt(0)
	v_mfma_f32_16x16x32_bf16 v[110:113], v[118:121], v[114:117], v[110:113]
	ds_read_b64_tr_b16 v[118:119], v178 offset:36960
	ds_read_b64_tr_b16 v[120:121], v179 offset:36960
	v_add_f32_e32 v1, v226, v1
	v_add_f32_e32 v1, v227, v1
	v_mfma_f32_16x16x32_bf16 v[106:109], v[122:125], v[114:117], v[106:109]
	v_add_f32_e32 v1, v228, v1
	v_add_f32_e32 v1, v229, v1
	v_add_f32_e32 v1, v230, v1
	s_waitcnt lgkmcnt(0)
	v_mfma_f32_16x16x32_bf16 v[98:101], v[118:121], v[114:117], v[98:101]
	ds_read_b64_tr_b16 v[120:121], v181 offset:36864
	ds_read_b64_tr_b16 v[124:125], v181 offset:36896
	ds_read_b64_tr_b16 v[118:119], v180 offset:36864
	ds_read_b64_tr_b16 v[122:123], v180 offset:36896
	v_cvt_pk_bf16_f32 v114, v218, v219
	v_cvt_pk_bf16_f32 v115, v220, v221
	v_cvt_pk_bf16_f32 v116, v222, v223
	v_cvt_pk_bf16_f32 v117, v224, v225
	v_fmamk_f32 v2, v93, 0x3e38aa3b, v209
	v_add_f32_e32 v1, v231, v1
	s_waitcnt lgkmcnt(1)
	v_mfma_f32_16x16x32_bf16 v[102:105], v[118:121], v[114:117], v[102:105]
	ds_read_b64_tr_b16 v[118:119], v180 offset:36928
	ds_read_b64_tr_b16 v[120:121], v181 offset:36928
	v_exp_f32_e32 v2, v2
	v_add_f32_e32 v1, v232, v1
	s_waitcnt lgkmcnt(0)
	v_mfma_f32_16x16x32_bf16 v[110:113], v[118:121], v[114:117], v[110:113]
	ds_read_b64_tr_b16 v[118:119], v180 offset:36960
	ds_read_b64_tr_b16 v[120:121], v181 offset:36960
	v_add_f32_e32 v1, v233, v1
	v_add_f32_e32 v1, v0, v1
	v_mfma_f32_16x16x32_bf16 v[106:109], v[122:125], v[114:117], v[106:109]
	v_add_f32_e32 v93, v2, v1
	v_fmamk_f32 v1, v94, 0x3e38aa3b, v209
	v_fmac_f32_e32 v209, 0x3e38aa3b, v95
	s_waitcnt lgkmcnt(0)
	v_mfma_f32_16x16x32_bf16 v[98:101], v[118:121], v[114:117], v[98:101]
	ds_read_b64_tr_b16 v[120:121], v183 offset:36864
	ds_read_b64_tr_b16 v[124:125], v183 offset:36896
	ds_read_b64_tr_b16 v[118:119], v182 offset:36864
	ds_read_b64_tr_b16 v[122:123], v182 offset:36896
	v_cvt_pk_bf16_f32 v114, v226, v227
	v_cvt_pk_bf16_f32 v115, v228, v229
	v_cvt_pk_bf16_f32 v116, v230, v231
	v_cvt_pk_bf16_f32 v117, v232, v233
	v_exp_f32_e32 v1, v1
	v_exp_f32_e32 v95, v209
	s_waitcnt lgkmcnt(1)
	v_mfma_f32_16x16x32_bf16 v[102:105], v[118:121], v[114:117], v[102:105]
	ds_read_b64_tr_b16 v[118:119], v182 offset:36928
	ds_read_b64_tr_b16 v[120:121], v183 offset:36928
	v_add_f32_e32 v93, v1, v93
	v_cvt_pk_bf16_f32 v1, v1, v95
	s_waitcnt lgkmcnt(0)
	v_mfma_f32_16x16x32_bf16 v[110:113], v[118:121], v[114:117], v[110:113]
	ds_read_b64_tr_b16 v[118:119], v182 offset:36960
	ds_read_b64_tr_b16 v[120:121], v183 offset:36960
	v_cvt_pk_bf16_f32 v0, v0, v2
	v_mov_b32_e32 v2, v3
	v_mfma_f32_16x16x32_bf16 v[106:109], v[122:125], v[114:117], v[106:109]
	v_add_f32_e32 v93, v95, v93
	v_mov_b32_e32 v94, v93
	s_nop 1
	v_permlane16_swap_b32_e32 v94, v93
	s_nop 0
	s_waitcnt lgkmcnt(0)
	v_add_f32_e32 v93, v93, v94
	v_mfma_f32_16x16x32_bf16 v[98:101], v[118:121], v[114:117], v[98:101]
	ds_read_b64_tr_b16 v[114:115], v184 offset:36864
	ds_read_b64_tr_b16 v[118:119], v184 offset:36896
	s_waitcnt lgkmcnt(1)
	v_mov_b32_e32 v116, v114
	v_mov_b32_e32 v117, v115
	s_waitcnt lgkmcnt(0)
	v_mov_b32_e32 v120, v118
	v_mov_b32_e32 v121, v119
	v_mfma_f32_16x16x32_bf16 v[102:105], v[114:117], v[0:3], v[102:105]
	ds_read_b64_tr_b16 v[114:115], v184 offset:36928
	v_mov_b32_e32 v94, v93
	s_nop 1
	v_permlane32_swap_b32_e32 v94, v93
	s_nop 0
	v_add_f32_e32 v93, v93, v94
	s_waitcnt lgkmcnt(0)
	v_mov_b32_e32 v116, v114
	v_mov_b32_e32 v117, v115
	v_mfma_f32_16x16x32_bf16 v[106:109], v[118:121], v[0:3], v[106:109]
	s_nop 0
	v_mfma_f32_16x16x32_bf16 v[110:113], v[114:117], v[0:3], v[110:113]
	ds_read_b64_tr_b16 v[114:115], v184 offset:36960
	s_waitcnt lgkmcnt(0)
	v_mov_b32_e32 v116, v114
	v_mov_b32_e32 v117, v115
	s_nop 1
	v_mfma_f32_16x16x32_bf16 v[98:101], v[114:117], v[0:3], v[98:101]
	v_div_scale_f32 v0, s[16:17], v93, v93, 1.0
	v_rcp_f32_e32 v1, v0
	s_nop 0
	v_fma_f32 v2, -v0, v1, 1.0
	v_fmac_f32_e32 v1, v2, v1
	v_div_scale_f32 v2, vcc, 1.0, v93, 1.0
	v_mul_f32_e32 v94, v2, v1
	v_fma_f32 v95, -v0, v94, v2
	v_fmac_f32_e32 v94, v95, v1
	v_fma_f32 v0, -v0, v94, v2
	v_div_fmas_f32 v0, v0, v1, v94
	v_div_fixup_f32 v94, v0, v93, 1.0
	v_lshlrev_b32_e32 v0, 9, v135
	v_and_b32_e32 v0, 0x7ffff000, v0
	v_bitop3_b32 v122, v206, v0, v96 bitop3:0xdc
	v_lshl_add_u32 v2, v97, v129, v122
	v_mov_b64_e32 v[0:1], s[78:79]
	v_mad_u64_u32 v[0:1], s[16:17], v2, s26, v[0:1]
	v_lshlrev_b32_e32 v2, 10, v131
	v_lshl_add_u64 v[96:97], v[0:1], 0, v[2:3]
	v_lshlrev_b32_e32 v2, 7, v208
	v_lshl_add_u64 v[96:97], v[96:97], 0, v[2:3]
	v_mov_b32_e32 v135, v3
	v_pk_mul_f32 v[102:103], v[102:103], v[94:95] op_sel_hi:[1,0]
	v_pk_mul_f32 v[104:105], v[104:105], v[94:95] op_sel_hi:[1,0]
	v_lshl_add_u64 v[96:97], v[96:97], 0, v[134:135]
	v_cvt_pk_bf16_f32 v102, v102, v103
	v_cvt_pk_bf16_f32 v103, v104, v105
	global_store_dwordx2 v[96:97], v[102:103], off
	v_pk_mul_f32 v[102:103], v[106:107], v[94:95] op_sel_hi:[1,0]
	v_pk_mul_f32 v[104:105], v[108:109], v[94:95] op_sel_hi:[1,0]
	v_cvt_pk_bf16_f32 v102, v102, v103
	v_cvt_pk_bf16_f32 v103, v104, v105
	global_store_dwordx2 v[96:97], v[102:103], off offset:32
	v_pk_mul_f32 v[102:103], v[110:111], v[94:95] op_sel_hi:[1,0]
	v_pk_mul_f32 v[104:105], v[112:113], v[94:95] op_sel_hi:[1,0]
	v_pk_mul_f32 v[98:99], v[98:99], v[94:95] op_sel_hi:[1,0]
	v_pk_mul_f32 v[94:95], v[100:101], v[94:95] op_sel_hi:[1,0]
	v_lshlrev_b32_e32 v2, 2, v208
	v_cvt_pk_bf16_f32 v102, v102, v103
	v_cvt_pk_bf16_f32 v103, v104, v105
	v_cvt_pk_bf16_f32 v98, v98, v99
	v_cvt_pk_bf16_f32 v99, v94, v95
	v_lshl_or_b32 v120, v131, 5, v2
	global_store_dwordx2 v[96:97], v[102:103], off offset:64
	global_store_dwordx2 v[96:97], v[98:99], off offset:96
	s_and_saveexec_b64 s[16:17], s[60:61]
	s_cbranch_execz .LBB0_1165
	v_cmp_gt_f32_e32 vcc, s75, v93
	v_mov_b32_e32 v121, v3
	v_lshl_add_u64 v[0:1], v[0:1], 0, v[120:121]
	v_cndmask_b32_e64 v2, 0, 32, vcc
	v_ldexp_f32 v2, v93, v2
	v_log_f32_e32 v2, v2
	s_nop 0
	v_mul_f32_e32 v93, 0x3f317217, v2
	v_fma_f32 v93, v2, s82, -v93
	v_fmac_f32_e32 v93, 0x3377d1cf, v2
	v_fmac_f32_e32 v93, 0x3f317217, v2
	v_cmp_lt_f32_e64 s[70:71], |v2|, s83
	s_nop 1
	v_cndmask_b32_e64 v2, v2, v93, s[70:71]
	v_cndmask_b32_e32 v93, 0, v204, vcc
	v_sub_f32_e32 v2, v2, v93
	v_fmac_f32_e32 v2, 0x3e000000, v92
	global_store_dword v[0:1], v2, off offset:3072

.LBB0_1167:
	s_or_b64 exec, exec, s[16:17]
	v_mov_b32_e32 v124, s74
	v_cndmask_b32_e64 v121, v84, v124, s[38:39]
	v_cndmask_b32_e64 v121, v121, v84, s[36:37]
	v_max3_f32 v84, v2, s74, v91
	v_max3_f32 v84, v84, v1, v0
	v_max3_f32 v84, v84, v116, v117
	v_max3_f32 v84, v84, v118, v119
	v_max3_f32 v84, v84, v112, v113
	v_max3_f32 v84, v84, v114, v115
	v_max3_f32 v84, v84, v108, v109
	v_max3_f32 v84, v84, v110, v111
	v_max3_f32 v84, v84, v104, v105
	v_max3_f32 v84, v84, v106, v107
	v_max3_f32 v84, v84, v100, v101
	v_max3_f32 v84, v84, v102, v103
	v_max3_f32 v84, v84, v92, v93
	v_max3_f32 v84, v84, v94, v95
	v_max3_f32 v84, v84, v96, v97
	v_cndmask_b32_e64 v85, v203, v85, s[36:37]
	v_max3_f32 v84, v84, v98, v99
	v_cndmask_b32_e64 v86, v86, v203, s[44:45]
	v_cndmask_b32_e64 v87, v87, v203, s[48:49]
	v_max3_f32 v84, v84, v121, v85
	v_max3_f32 v84, v84, v86, v87
	v_mov_b32_e32 v123, v84
	s_nop 1
	v_permlane16_swap_b32_e32 v123, v84
	s_nop 0
	v_lshlrev_b32_e32 v89, 9, v131
	v_or_b32_e32 v90, v207, v137
	v_lshlrev_b32_e32 v88, 6, v208
	s_waitcnt lgkmcnt(0)
	v_max_f32_e32 v123, v123, v123
	v_max_f32_e32 v84, v84, v123
	v_mov_b32_e32 v123, v84
	s_nop 1
	v_permlane32_swap_b32_e32 v123, v84
	s_nop 0
	v_max_f32_e32 v123, v123, v123
	v_max_f32_e32 v84, v84, v123
	v_mul_f32_e32 v123, 0xbe38aa3b, v84
	v_fmamk_f32 v2, v2, 0x3e38aa3b, v123
	v_exp_f32_e32 v2, v2
	v_fmamk_f32 v91, v91, 0x3e38aa3b, v123
	v_exp_f32_e32 v91, v91
	v_fmamk_f32 v1, v1, 0x3e38aa3b, v123
	v_exp_f32_e32 v1, v1
	v_fmamk_f32 v0, v0, 0x3e38aa3b, v123
	v_exp_f32_e32 v0, v0
	v_fmamk_f32 v116, v116, 0x3e38aa3b, v123
	v_add_f32_e32 v124, 0, v2
	v_exp_f32_e32 v116, v116
	v_fmamk_f32 v117, v117, 0x3e38aa3b, v123
	v_add_f32_e32 v124, v91, v124
	v_exp_f32_e32 v117, v117
	v_fmamk_f32 v118, v118, 0x3e38aa3b, v123
	v_add_f32_e32 v124, v1, v124
	v_exp_f32_e32 v118, v118
	v_fmamk_f32 v119, v119, 0x3e38aa3b, v123
	v_add_f32_e32 v124, v0, v124
	v_exp_f32_e32 v119, v119
	v_fmamk_f32 v112, v112, 0x3e38aa3b, v123
	v_add_f32_e32 v124, v116, v124
	v_exp_f32_e32 v112, v112
	v_fmamk_f32 v113, v113, 0x3e38aa3b, v123
	v_add_f32_e32 v124, v117, v124
	v_exp_f32_e32 v113, v113
	v_fmamk_f32 v114, v114, 0x3e38aa3b, v123
	v_add_f32_e32 v124, v118, v124
	v_exp_f32_e32 v114, v114
	v_fmamk_f32 v115, v115, 0x3e38aa3b, v123
	v_add_f32_e32 v124, v119, v124
	v_exp_f32_e32 v115, v115
	v_fmamk_f32 v108, v108, 0x3e38aa3b, v123
	v_add_f32_e32 v124, v112, v124
	v_exp_f32_e32 v125, v108
	v_add_f32_e32 v124, v113, v124
	v_add_f32_e32 v124, v114, v124
	v_add_f32_e32 v124, v115, v124
	v_fmamk_f32 v109, v109, 0x3e38aa3b, v123
	v_add_f32_e32 v108, v125, v124
	v_exp_f32_e32 v124, v109
	v_fmamk_f32 v109, v110, 0x3e38aa3b, v123
	v_exp_f32_e32 v126, v109
	v_fmamk_f32 v109, v111, 0x3e38aa3b, v123
	v_exp_f32_e32 v127, v109
	v_fmamk_f32 v104, v104, 0x3e38aa3b, v123
	v_exp_f32_e32 v131, v104
	v_fmamk_f32 v105, v105, 0x3e38aa3b, v123
	v_add_f32_e32 v108, v124, v108
	v_exp_f32_e32 v135, v105
	v_fmamk_f32 v105, v106, 0x3e38aa3b, v123
	v_add_f32_e32 v108, v126, v108
	v_exp_f32_e32 v206, v105
	v_fmamk_f32 v105, v107, 0x3e38aa3b, v123
	v_add_f32_e32 v108, v127, v108
	v_exp_f32_e32 v207, v105
	v_fmamk_f32 v100, v100, 0x3e38aa3b, v123
	v_add_f32_e32 v104, v131, v108
	v_exp_f32_e32 v208, v100
	v_fmamk_f32 v101, v101, 0x3e38aa3b, v123
	v_add_f32_e32 v104, v135, v104
	v_exp_f32_e32 v209, v101
	v_fmamk_f32 v101, v102, 0x3e38aa3b, v123
	v_add_f32_e32 v104, v206, v104
	v_exp_f32_e32 v210, v101
	v_fmamk_f32 v101, v103, 0x3e38aa3b, v123
	v_add_f32_e32 v104, v207, v104
	v_exp_f32_e32 v211, v101
	v_fmamk_f32 v92, v92, 0x3e38aa3b, v123
	v_add_f32_e32 v100, v208, v104
	v_exp_f32_e32 v212, v92
	v_fmamk_f32 v93, v93, 0x3e38aa3b, v123
	v_add_f32_e32 v100, v209, v100
	v_exp_f32_e32 v213, v93
	v_fmamk_f32 v93, v94, 0x3e38aa3b, v123
	v_add_f32_e32 v100, v210, v100
	v_exp_f32_e32 v214, v93
	v_fmamk_f32 v93, v95, 0x3e38aa3b, v123
	v_add_f32_e32 v100, v211, v100
	v_exp_f32_e32 v215, v93
	v_fmamk_f32 v93, v96, 0x3e38aa3b, v123
	v_add_f32_e32 v92, v212, v100
	v_exp_f32_e32 v216, v93
	v_fmamk_f32 v93, v97, 0x3e38aa3b, v123
	v_add_f32_e32 v92, v213, v92
	v_exp_f32_e32 v217, v93
	v_fmamk_f32 v93, v98, 0x3e38aa3b, v123
	v_add_f32_e32 v92, v214, v92
	v_exp_f32_e32 v218, v93
	v_fmamk_f32 v93, v99, 0x3e38aa3b, v123
	v_add_f32_e32 v92, v215, v92
	v_exp_f32_e32 v219, v93
	v_fmamk_f32 v93, v121, 0x3e38aa3b, v123
	v_add_f32_e32 v92, v216, v92
	v_exp_f32_e32 v121, v93
	v_fmamk_f32 v85, v85, 0x3e38aa3b, v123
	v_add_f32_e32 v92, v217, v92
	v_exp_f32_e32 v220, v85
	ds_read_b64_tr_b16 v[98:99], v195 offset:36864
	ds_read_b64_tr_b16 v[102:103], v195 offset:36896
	ds_read_b64_tr_b16 v[96:97], v194 offset:36864
	ds_read_b64_tr_b16 v[100:101], v194 offset:36896
	ds_read_b64_tr_b16 v[104:105], v194 offset:36928
	ds_read_b64_tr_b16 v[106:107], v195 offset:36928
	ds_read_b64_tr_b16 v[108:109], v194 offset:36960
	ds_read_b64_tr_b16 v[110:111], v195 offset:36960
	v_add_f32_e32 v92, v218, v92
	v_add_f32_e32 v92, v219, v92
	v_add_f32_e32 v92, v121, v92
	v_add_f32_e32 v85, v220, v92
	v_cvt_pk_bf16_f32 v92, v2, v91
	v_cvt_pk_bf16_f32 v93, v1, v0
	v_cvt_pk_bf16_f32 v94, v116, v117
	v_cvt_pk_bf16_f32 v95, v118, v119
	v_fmamk_f32 v86, v86, 0x3e38aa3b, v123
	v_fmac_f32_e32 v123, 0x3e38aa3b, v87
	s_waitcnt lgkmcnt(5)
	v_mfma_f32_16x16x32_bf16 v[96:99], v[96:99], v[92:95], 0
	v_exp_f32_e32 v221, v86
	v_exp_f32_e32 v87, v123
	v_cvt_pk_bf16_f32 v0, v121, v220
	s_waitcnt lgkmcnt(4)
	v_mfma_f32_16x16x32_bf16 v[100:103], v[100:103], v[92:95], 0
	v_mov_b32_e32 v2, v3
	v_cvt_pk_bf16_f32 v1, v221, v87
	v_add_f32_e32 v85, v221, v85
	s_waitcnt lgkmcnt(2)
	v_mfma_f32_16x16x32_bf16 v[104:107], v[104:107], v[92:95], 0
	v_add_f32_e32 v85, v87, v85
	v_mov_b32_e32 v86, v85
	s_nop 1
	v_permlane16_swap_b32_e32 v86, v85
	s_nop 0
	s_waitcnt lgkmcnt(0)
	v_add_f32_e32 v85, v85, v86
	v_mfma_f32_16x16x32_bf16 v[92:95], v[108:111], v[92:95], 0
	v_cvt_pk_bf16_f32 v108, v112, v113
	v_cvt_pk_bf16_f32 v109, v114, v115
	ds_read_b64_tr_b16 v[114:115], v197 offset:36864
	ds_read_b64_tr_b16 v[118:119], v197 offset:36896
	ds_read_b64_tr_b16 v[112:113], v196 offset:36864
	ds_read_b64_tr_b16 v[116:117], v196 offset:36896
	v_cvt_pk_bf16_f32 v110, v125, v124
	v_cvt_pk_bf16_f32 v111, v126, v127
	v_mov_b32_e32 v86, v85
	s_nop 1
	v_permlane32_swap_b32_e32 v86, v85
	s_nop 0
	s_waitcnt lgkmcnt(0)
	v_add_f32_e32 v85, v85, v86
	v_mfma_f32_16x16x32_bf16 v[96:99], v[112:115], v[108:111], v[96:99]
	ds_read_b64_tr_b16 v[112:113], v196 offset:36928
	ds_read_b64_tr_b16 v[114:115], v197 offset:36928
	s_waitcnt lgkmcnt(0)
	v_mfma_f32_16x16x32_bf16 v[104:107], v[112:115], v[108:111], v[104:107]
	ds_read_b64_tr_b16 v[112:113], v196 offset:36960
	ds_read_b64_tr_b16 v[114:115], v197 offset:36960
	v_mfma_f32_16x16x32_bf16 v[100:103], v[116:119], v[108:111], v[100:103]
	s_waitcnt lgkmcnt(0)
	v_mfma_f32_16x16x32_bf16 v[92:95], v[112:115], v[108:111], v[92:95]
	ds_read_b64_tr_b16 v[114:115], v199 offset:36864
	ds_read_b64_tr_b16 v[118:119], v199 offset:36896
	ds_read_b64_tr_b16 v[112:113], v198 offset:36864
	ds_read_b64_tr_b16 v[116:117], v198 offset:36896
	v_cvt_pk_bf16_f32 v108, v131, v135
	v_cvt_pk_bf16_f32 v109, v206, v207
	v_cvt_pk_bf16_f32 v110, v208, v209
	v_cvt_pk_bf16_f32 v111, v210, v211
	v_mov_b32_e32 v135, v3
	s_waitcnt lgkmcnt(1)
	v_mfma_f32_16x16x32_bf16 v[96:99], v[112:115], v[108:111], v[96:99]
	ds_read_b64_tr_b16 v[112:113], v198 offset:36928
	ds_read_b64_tr_b16 v[114:115], v199 offset:36928
	s_waitcnt lgkmcnt(0)
	v_mfma_f32_16x16x32_bf16 v[104:107], v[112:115], v[108:111], v[104:107]
	ds_read_b64_tr_b16 v[112:113], v198 offset:36960
	ds_read_b64_tr_b16 v[114:115], v199 offset:36960
	v_mfma_f32_16x16x32_bf16 v[100:103], v[116:119], v[108:111], v[100:103]
	s_waitcnt lgkmcnt(0)
	v_mfma_f32_16x16x32_bf16 v[92:95], v[112:115], v[108:111], v[92:95]
	ds_read_b64_tr_b16 v[114:115], v201 offset:36864
	ds_read_b64_tr_b16 v[118:119], v201 offset:36896
	ds_read_b64_tr_b16 v[112:113], v200 offset:36864
	ds_read_b64_tr_b16 v[116:117], v200 offset:36896
	v_cvt_pk_bf16_f32 v108, v212, v213
	v_cvt_pk_bf16_f32 v109, v214, v215
	v_cvt_pk_bf16_f32 v110, v216, v217
	v_cvt_pk_bf16_f32 v111, v218, v219
	s_waitcnt lgkmcnt(1)
	s_nop 0
	v_mfma_f32_16x16x32_bf16 v[96:99], v[112:115], v[108:111], v[96:99]
	ds_read_b64_tr_b16 v[112:113], v200 offset:36928
	ds_read_b64_tr_b16 v[114:115], v201 offset:36928
	s_waitcnt lgkmcnt(0)
	v_mfma_f32_16x16x32_bf16 v[104:107], v[112:115], v[108:111], v[104:107]
	ds_read_b64_tr_b16 v[112:113], v200 offset:36960
	ds_read_b64_tr_b16 v[114:115], v201 offset:36960
	v_mfma_f32_16x16x32_bf16 v[100:103], v[116:119], v[108:111], v[100:103]
	s_waitcnt lgkmcnt(0)
	v_mfma_f32_16x16x32_bf16 v[92:95], v[112:115], v[108:111], v[92:95]
	ds_read_b64_tr_b16 v[108:109], v202 offset:36864
	ds_read_b64_tr_b16 v[112:113], v202 offset:36896
	s_waitcnt lgkmcnt(1)
	v_mov_b32_e32 v110, v108
	v_mov_b32_e32 v111, v109
	s_waitcnt lgkmcnt(0)
	v_mov_b32_e32 v114, v112
	v_mov_b32_e32 v115, v113
	v_mfma_f32_16x16x32_bf16 v[96:99], v[108:111], v[0:3], v[96:99]
	ds_read_b64_tr_b16 v[108:109], v202 offset:36928
	s_waitcnt lgkmcnt(0)
	v_mov_b32_e32 v110, v108
	v_mov_b32_e32 v111, v109
	v_mfma_f32_16x16x32_bf16 v[100:103], v[112:115], v[0:3], v[100:103]
	s_nop 0
	v_mfma_f32_16x16x32_bf16 v[104:107], v[108:111], v[0:3], v[104:107]
	ds_read_b64_tr_b16 v[108:109], v202 offset:36960
	s_waitcnt lgkmcnt(0)
	v_mov_b32_e32 v110, v108
	v_mov_b32_e32 v111, v109
	s_nop 1
	v_mfma_f32_16x16x32_bf16 v[92:95], v[108:111], v[0:3], v[92:95]
	v_div_scale_f32 v0, s[16:17], v85, v85, 1.0
	v_rcp_f32_e32 v1, v0
	s_nop 0
	v_fma_f32 v2, -v0, v1, 1.0
	v_fmac_f32_e32 v1, v2, v1
	v_div_scale_f32 v2, vcc, 1.0, v85, 1.0
	v_mul_f32_e32 v86, v2, v1
	v_fma_f32 v87, -v0, v86, v2
	v_fmac_f32_e32 v86, v87, v1
	v_fma_f32 v0, -v0, v86, v2
	v_div_fmas_f32 v0, v0, v1, v86
	v_div_fixup_f32 v86, v0, v85, 1.0
	v_lshl_add_u32 v2, v90, v129, v122
	v_mov_b64_e32 v[0:1], s[78:79]
	v_mad_u64_u32 v[0:1], s[16:17], v2, s26, v[0:1]
	v_lshlrev_b32_e32 v2, 1, v89
	v_lshl_add_u64 v[90:91], v[0:1], 0, v[2:3]
	v_lshlrev_b32_e32 v2, 1, v88
	v_lshl_add_u64 v[88:89], v[90:91], 0, v[2:3]
	v_pk_mul_f32 v[90:91], v[96:97], v[86:87] op_sel_hi:[1,0]
	v_pk_mul_f32 v[96:97], v[98:99], v[86:87] op_sel_hi:[1,0]
	v_lshl_add_u64 v[88:89], v[88:89], 0, v[134:135]
	v_cvt_pk_bf16_f32 v90, v90, v91
	v_cvt_pk_bf16_f32 v91, v96, v97
	global_store_dwordx2 v[88:89], v[90:91], off
	v_pk_mul_f32 v[90:91], v[100:101], v[86:87] op_sel_hi:[1,0]
	v_pk_mul_f32 v[96:97], v[102:103], v[86:87] op_sel_hi:[1,0]
	v_cvt_pk_bf16_f32 v90, v90, v91
	v_cvt_pk_bf16_f32 v91, v96, v97
	global_store_dwordx2 v[88:89], v[90:91], off offset:32
	v_pk_mul_f32 v[90:91], v[104:105], v[86:87] op_sel_hi:[1,0]
	v_pk_mul_f32 v[96:97], v[106:107], v[86:87] op_sel_hi:[1,0]
	v_cvt_pk_bf16_f32 v90, v90, v91
	v_cvt_pk_bf16_f32 v91, v96, v97
	global_store_dwordx2 v[88:89], v[90:91], off offset:64
	v_pk_mul_f32 v[90:91], v[92:93], v[86:87] op_sel_hi:[1,0]
	v_pk_mul_f32 v[86:87], v[94:95], v[86:87] op_sel_hi:[1,0]
	v_cvt_pk_bf16_f32 v90, v90, v91
	v_cvt_pk_bf16_f32 v91, v86, v87
	global_store_dwordx2 v[88:89], v[90:91], off offset:96
	s_and_saveexec_b64 s[16:17], s[60:61]
	s_cbranch_execz .LBB0_1150
	v_cmp_gt_f32_e32 vcc, s75, v85
	v_mov_b32_e32 v121, v3
	v_lshl_add_u64 v[0:1], v[0:1], 0, v[120:121]
	v_cndmask_b32_e64 v2, 0, 32, vcc
	v_ldexp_f32 v2, v85, v2
	v_log_f32_e32 v2, v2
	s_nop 0
	v_mul_f32_e32 v85, 0x3f317217, v2
	v_fma_f32 v85, v2, s82, -v85
	v_fmac_f32_e32 v85, 0x3377d1cf, v2
	v_fmac_f32_e32 v85, 0x3f317217, v2
	v_cmp_lt_f32_e64 s[66:67], |v2|, s83
	s_nop 1
	v_cndmask_b32_e64 v2, v2, v85, s[66:67]
	v_cndmask_b32_e32 v85, 0, v204, vcc
	v_sub_f32_e32 v2, v2, v85
	v_fmac_f32_e32 v2, 0x3e000000, v84
	global_store_dword v[0:1], v2, off offset:3072
	s_branch .LBB0_1150
